# MLA 16x16x32 loop software-pipelined: softmax VALU in MFMA gaps, PV tail deferred across barrier with DMA in its gaps
# speedup vs baseline: 1.0614x; 1.0116x over previous
.Lmla_unit:
	s_and_b32 s77, s76, 7
	s_lshr_b32 s78, s76, 3
	s_lshl_b32 s78, s78, 8
	s_lshl_b32 s0, s77, 4
	v_mov_b32_e32 v217, s0
	global_load_dwordx4 v[218:221], v217, s[28:29] offset:384
	global_load_dwordx2 v[222:223], v249, s[28:29] offset:640
	s_add_i32 s0, s78, 0
	s_lshl_b32 s1, s33, 5
	s_add_i32 s0, s0, s1
	s_mul_i32 s1, s0, 0xc00
	s_mul_i32 s3, s77, 0x180
	s_add_u32 s1, s1, s3
	s_add_u32 s16, s28, 404750336
	s_addc_u32 s17, s29, 0
	s_add_u32 s16, s16, s1
	s_addc_u32 s17, s17, 0
	s_lshl_b32 s1, s0, 12
	s_lshl_b32 s3, s77, 8
	s_add_u32 s1, s1, s3
	s_add_u32 s1, s1, 0x800
	s_add_u32 s18, s28, 102760448
	s_addc_u32 s19, s29, 0
	s_add_u32 s18, s18, s1
	s_addc_u32 s19, s19, 0
	s_mul_i32 s1, s77, 0x180
	s_add_u32 s4, s28, 455081984
	s_addc_u32 s5, s29, 0
	s_add_u32 s4, s4, s1
	s_addc_u32 s5, s5, 0
	s_and_b32 s5, s5, 0xffff
	s_lshl_b32 s1, s77, 8
	s_add_u32 s8, s28, 262144000
	s_addc_u32 s9, s29, 0
	s_add_u32 s8, s8, s1
	s_addc_u32 s9, s9, 0
	s_and_b32 s9, s9, 0xffff
	s_mul_i32 s1, s77, 0x180
	s_sub_u32 s6, 50331648, s1
	s_lshl_b32 s1, s77, 8
	s_sub_u32 s10, 33554432, s1
	s_mov_b32 s12, 0
	s_mov_b32 s13, 0
	s_mov_b32 m0, s46
	s_nop 0
	buffer_load_dwordx4 v210, s[4:7], s12 offen lds
	s_mov_b32 m0, s47
	s_nop 0
	buffer_load_dwordx4 v211, s[4:7], s12 offen lds
	s_mov_b32 m0, s48
	s_nop 0
	buffer_load_dwordx4 v212, s[4:7], s12 offen lds
	s_mov_b32 m0, s52
	s_nop 0
	buffer_load_dwordx4 v213, s[8:11], s13 offen lds
	s_mov_b32 m0, s53
	s_nop 0
	buffer_load_dwordx4 v214, s[8:11], s13 offen lds
	s_add_i32 s12, s12, 0x30000
	s_add_i32 s13, s13, 0x20000
	global_load_dwordx4 v[112:115], v215, s[16:17] offset:0
	global_load_dwordx4 v[116:119], v215, s[16:17] offset:64
	global_load_dwordx4 v[120:123], v215, s[16:17] offset:128
	global_load_dwordx4 v[124:127], v215, s[16:17] offset:192
	global_load_dwordx4 v[128:131], v215, s[16:17] offset:256
	global_load_dwordx4 v[132:135], v215, s[16:17] offset:320
	global_load_dwordx4 v[136:139], v216, s[16:17] offset:0
	global_load_dwordx4 v[140:143], v216, s[16:17] offset:64
	global_load_dwordx4 v[144:147], v216, s[16:17] offset:128
	global_load_dwordx4 v[148:151], v216, s[16:17] offset:192
	global_load_dwordx4 v[152:155], v216, s[16:17] offset:256
	global_load_dwordx4 v[156:159], v216, s[16:17] offset:320
	v_mov_b32_e32 v0, 0
	v_mov_b32_e32 v1, 0
	v_mov_b32_e32 v2, 0
	v_mov_b32_e32 v3, 0
	v_mov_b32_e32 v4, 0
	v_mov_b32_e32 v5, 0
	v_mov_b32_e32 v6, 0
	v_mov_b32_e32 v7, 0
	v_mov_b32_e32 v8, 0
	v_mov_b32_e32 v9, 0
	v_mov_b32_e32 v10, 0
	v_mov_b32_e32 v11, 0
	v_mov_b32_e32 v12, 0
	v_mov_b32_e32 v13, 0
	v_mov_b32_e32 v14, 0
	v_mov_b32_e32 v15, 0
	v_mov_b32_e32 v16, 0
	v_mov_b32_e32 v17, 0
	v_mov_b32_e32 v18, 0
	v_mov_b32_e32 v19, 0
	v_mov_b32_e32 v20, 0
	v_mov_b32_e32 v21, 0
	v_mov_b32_e32 v22, 0
	v_mov_b32_e32 v23, 0
	v_mov_b32_e32 v24, 0
	v_mov_b32_e32 v25, 0
	v_mov_b32_e32 v26, 0
	v_mov_b32_e32 v27, 0
	v_mov_b32_e32 v28, 0
	v_mov_b32_e32 v29, 0
	v_mov_b32_e32 v30, 0
	v_mov_b32_e32 v31, 0
	v_mov_b32_e32 v32, 0
	v_mov_b32_e32 v33, 0
	v_mov_b32_e32 v34, 0
	v_mov_b32_e32 v35, 0
	v_mov_b32_e32 v36, 0
	v_mov_b32_e32 v37, 0
	v_mov_b32_e32 v38, 0
	v_mov_b32_e32 v39, 0
	v_mov_b32_e32 v40, 0
	v_mov_b32_e32 v41, 0
	v_mov_b32_e32 v42, 0
	v_mov_b32_e32 v43, 0
	v_mov_b32_e32 v44, 0
	v_mov_b32_e32 v45, 0
	v_mov_b32_e32 v46, 0
	v_mov_b32_e32 v47, 0
	v_mov_b32_e32 v48, 0
	v_mov_b32_e32 v49, 0
	v_mov_b32_e32 v50, 0
	v_mov_b32_e32 v51, 0
	v_mov_b32_e32 v52, 0
	v_mov_b32_e32 v53, 0
	v_mov_b32_e32 v54, 0
	v_mov_b32_e32 v55, 0
	v_mov_b32_e32 v56, 0
	v_mov_b32_e32 v57, 0
	v_mov_b32_e32 v58, 0
	v_mov_b32_e32 v59, 0
	v_mov_b32_e32 v60, 0
	v_mov_b32_e32 v61, 0
	v_mov_b32_e32 v62, 0
	v_mov_b32_e32 v63, 0
	v_mov_b32_e32 v200, 0
	v_mov_b32_e32 v201, 0
	v_mov_b32_e32 v184, 0
	v_mov_b32_e32 v185, 0
	v_mov_b32_e32 v186, 0
	v_mov_b32_e32 v187, 0
	v_mov_b32_e32 v188, 0
	v_mov_b32_e32 v189, 0
	v_mov_b32_e32 v190, 0
	v_mov_b32_e32 v191, 0
	v_mov_b32_e32 v192, 0
	v_mov_b32_e32 v193, 0
	v_mov_b32_e32 v194, 0
	v_mov_b32_e32 v195, 0
	v_mov_b32_e32 v196, 0
	v_mov_b32_e32 v197, 0
	v_mov_b32_e32 v198, 0
	v_mov_b32_e32 v199, 0
	v_mov_b32_e32 v96, 0
	v_mov_b32_e32 v97, 0
	v_mov_b32_e32 v98, 0
	v_mov_b32_e32 v99, 0
	v_mov_b32_e32 v100, 0
	v_mov_b32_e32 v101, 0
	v_mov_b32_e32 v102, 0
	v_mov_b32_e32 v103, 0
	v_mov_b32_e32 v104, 0
	v_mov_b32_e32 v105, 0
	v_mov_b32_e32 v106, 0
	v_mov_b32_e32 v107, 0
	v_mov_b32_e32 v108, 0
	v_mov_b32_e32 v109, 0
	v_mov_b32_e32 v110, 0
	v_mov_b32_e32 v111, 0
	s_waitcnt vmcnt(0)
	v_add_f32_e32 v218, v218, v219
	v_add_f32_e32 v220, v220, v221
	v_add_f32_e32 v222, v222, v223
	v_add_f32_e32 v218, v218, v220
	v_add_f32_e32 v218, v218, v222
	v_sqrt_f32_e32 v218, v218
	s_nop 0
	v_readfirstlane_b32 s60, v218
	v_mov_b32_e32 v224, 0
	v_lshlrev_b32_e32 v226, 16, v112
	v_and_b32_e32 v227, 0xffff0000, v112
	v_fmac_f32_e32 v224, v226, v226
	v_fmac_f32_e32 v224, v227, v227
	v_lshlrev_b32_e32 v226, 16, v113
	v_and_b32_e32 v227, 0xffff0000, v113
	v_fmac_f32_e32 v224, v226, v226
	v_fmac_f32_e32 v224, v227, v227
	v_lshlrev_b32_e32 v226, 16, v114
	v_and_b32_e32 v227, 0xffff0000, v114
	v_fmac_f32_e32 v224, v226, v226
	v_fmac_f32_e32 v224, v227, v227
	v_lshlrev_b32_e32 v226, 16, v115
	v_and_b32_e32 v227, 0xffff0000, v115
	v_fmac_f32_e32 v224, v226, v226
	v_fmac_f32_e32 v224, v227, v227
	v_lshlrev_b32_e32 v226, 16, v116
	v_and_b32_e32 v227, 0xffff0000, v116
	v_fmac_f32_e32 v224, v226, v226
	v_fmac_f32_e32 v224, v227, v227
	v_lshlrev_b32_e32 v226, 16, v117
	v_and_b32_e32 v227, 0xffff0000, v117
	v_fmac_f32_e32 v224, v226, v226
	v_fmac_f32_e32 v224, v227, v227
	v_lshlrev_b32_e32 v226, 16, v118
	v_and_b32_e32 v227, 0xffff0000, v118
	v_fmac_f32_e32 v224, v226, v226
	v_fmac_f32_e32 v224, v227, v227
	v_lshlrev_b32_e32 v226, 16, v119
	v_and_b32_e32 v227, 0xffff0000, v119
	v_fmac_f32_e32 v224, v226, v226
	v_fmac_f32_e32 v224, v227, v227
	v_lshlrev_b32_e32 v226, 16, v120
	v_and_b32_e32 v227, 0xffff0000, v120
	v_fmac_f32_e32 v224, v226, v226
	v_fmac_f32_e32 v224, v227, v227
	v_lshlrev_b32_e32 v226, 16, v121
	v_and_b32_e32 v227, 0xffff0000, v121
	v_fmac_f32_e32 v224, v226, v226
	v_fmac_f32_e32 v224, v227, v227
	v_lshlrev_b32_e32 v226, 16, v122
	v_and_b32_e32 v227, 0xffff0000, v122
	v_fmac_f32_e32 v224, v226, v226
	v_fmac_f32_e32 v224, v227, v227
	v_lshlrev_b32_e32 v226, 16, v123
	v_and_b32_e32 v227, 0xffff0000, v123
	v_fmac_f32_e32 v224, v226, v226
	v_fmac_f32_e32 v224, v227, v227
	v_lshlrev_b32_e32 v226, 16, v124
	v_and_b32_e32 v227, 0xffff0000, v124
	v_fmac_f32_e32 v224, v226, v226
	v_fmac_f32_e32 v224, v227, v227
	v_lshlrev_b32_e32 v226, 16, v125
	v_and_b32_e32 v227, 0xffff0000, v125
	v_fmac_f32_e32 v224, v226, v226
	v_fmac_f32_e32 v224, v227, v227
	v_lshlrev_b32_e32 v226, 16, v126
	v_and_b32_e32 v227, 0xffff0000, v126
	v_fmac_f32_e32 v224, v226, v226
	v_fmac_f32_e32 v224, v227, v227
	v_lshlrev_b32_e32 v226, 16, v127
	v_and_b32_e32 v227, 0xffff0000, v127
	v_fmac_f32_e32 v224, v226, v226
	v_fmac_f32_e32 v224, v227, v227
	v_lshlrev_b32_e32 v226, 16, v128
	v_and_b32_e32 v227, 0xffff0000, v128
	v_fmac_f32_e32 v224, v226, v226
	v_fmac_f32_e32 v224, v227, v227
	v_lshlrev_b32_e32 v226, 16, v129
	v_and_b32_e32 v227, 0xffff0000, v129
	v_fmac_f32_e32 v224, v226, v226
	v_fmac_f32_e32 v224, v227, v227
	v_lshlrev_b32_e32 v226, 16, v130
	v_and_b32_e32 v227, 0xffff0000, v130
	v_fmac_f32_e32 v224, v226, v226
	v_fmac_f32_e32 v224, v227, v227
	v_lshlrev_b32_e32 v226, 16, v131
	v_and_b32_e32 v227, 0xffff0000, v131
	v_fmac_f32_e32 v224, v226, v226
	v_fmac_f32_e32 v224, v227, v227
	v_lshlrev_b32_e32 v226, 16, v132
	v_and_b32_e32 v227, 0xffff0000, v132
	v_fmac_f32_e32 v224, v226, v226
	v_fmac_f32_e32 v224, v227, v227
	v_lshlrev_b32_e32 v226, 16, v133
	v_and_b32_e32 v227, 0xffff0000, v133
	v_fmac_f32_e32 v224, v226, v226
	v_fmac_f32_e32 v224, v227, v227
	v_lshlrev_b32_e32 v226, 16, v134
	v_and_b32_e32 v227, 0xffff0000, v134
	v_fmac_f32_e32 v224, v226, v226
	v_fmac_f32_e32 v224, v227, v227
	v_lshlrev_b32_e32 v226, 16, v135
	v_and_b32_e32 v227, 0xffff0000, v135
	v_fmac_f32_e32 v224, v226, v226
	v_fmac_f32_e32 v224, v227, v227
	ds_write_b32 v245, v224 offset:0
	v_mov_b32_e32 v225, 0
	v_lshlrev_b32_e32 v226, 16, v136
	v_and_b32_e32 v227, 0xffff0000, v136
	v_fmac_f32_e32 v225, v226, v226
	v_fmac_f32_e32 v225, v227, v227
	v_lshlrev_b32_e32 v226, 16, v137
	v_and_b32_e32 v227, 0xffff0000, v137
	v_fmac_f32_e32 v225, v226, v226
	v_fmac_f32_e32 v225, v227, v227
	v_lshlrev_b32_e32 v226, 16, v138
	v_and_b32_e32 v227, 0xffff0000, v138
	v_fmac_f32_e32 v225, v226, v226
	v_fmac_f32_e32 v225, v227, v227
	v_lshlrev_b32_e32 v226, 16, v139
	v_and_b32_e32 v227, 0xffff0000, v139
	v_fmac_f32_e32 v225, v226, v226
	v_fmac_f32_e32 v225, v227, v227
	v_lshlrev_b32_e32 v226, 16, v140
	v_and_b32_e32 v227, 0xffff0000, v140
	v_fmac_f32_e32 v225, v226, v226
	v_fmac_f32_e32 v225, v227, v227
	v_lshlrev_b32_e32 v226, 16, v141
	v_and_b32_e32 v227, 0xffff0000, v141
	v_fmac_f32_e32 v225, v226, v226
	v_fmac_f32_e32 v225, v227, v227
	v_lshlrev_b32_e32 v226, 16, v142
	v_and_b32_e32 v227, 0xffff0000, v142
	v_fmac_f32_e32 v225, v226, v226
	v_fmac_f32_e32 v225, v227, v227
	v_lshlrev_b32_e32 v226, 16, v143
	v_and_b32_e32 v227, 0xffff0000, v143
	v_fmac_f32_e32 v225, v226, v226
	v_fmac_f32_e32 v225, v227, v227
	v_lshlrev_b32_e32 v226, 16, v144
	v_and_b32_e32 v227, 0xffff0000, v144
	v_fmac_f32_e32 v225, v226, v226
	v_fmac_f32_e32 v225, v227, v227
	v_lshlrev_b32_e32 v226, 16, v145
	v_and_b32_e32 v227, 0xffff0000, v145
	v_fmac_f32_e32 v225, v226, v226
	v_fmac_f32_e32 v225, v227, v227
	v_lshlrev_b32_e32 v226, 16, v146
	v_and_b32_e32 v227, 0xffff0000, v146
	v_fmac_f32_e32 v225, v226, v226
	v_fmac_f32_e32 v225, v227, v227
	v_lshlrev_b32_e32 v226, 16, v147
	v_and_b32_e32 v227, 0xffff0000, v147
	v_fmac_f32_e32 v225, v226, v226
	v_fmac_f32_e32 v225, v227, v227
	v_lshlrev_b32_e32 v226, 16, v148
	v_and_b32_e32 v227, 0xffff0000, v148
	v_fmac_f32_e32 v225, v226, v226
	v_fmac_f32_e32 v225, v227, v227
	v_lshlrev_b32_e32 v226, 16, v149
	v_and_b32_e32 v227, 0xffff0000, v149
	v_fmac_f32_e32 v225, v226, v226
	v_fmac_f32_e32 v225, v227, v227
	v_lshlrev_b32_e32 v226, 16, v150
	v_and_b32_e32 v227, 0xffff0000, v150
	v_fmac_f32_e32 v225, v226, v226
	v_fmac_f32_e32 v225, v227, v227
	v_lshlrev_b32_e32 v226, 16, v151
	v_and_b32_e32 v227, 0xffff0000, v151
	v_fmac_f32_e32 v225, v226, v226
	v_fmac_f32_e32 v225, v227, v227
	v_lshlrev_b32_e32 v226, 16, v152
	v_and_b32_e32 v227, 0xffff0000, v152
	v_fmac_f32_e32 v225, v226, v226
	v_fmac_f32_e32 v225, v227, v227
	v_lshlrev_b32_e32 v226, 16, v153
	v_and_b32_e32 v227, 0xffff0000, v153
	v_fmac_f32_e32 v225, v226, v226
	v_fmac_f32_e32 v225, v227, v227
	v_lshlrev_b32_e32 v226, 16, v154
	v_and_b32_e32 v227, 0xffff0000, v154
	v_fmac_f32_e32 v225, v226, v226
	v_fmac_f32_e32 v225, v227, v227
	v_lshlrev_b32_e32 v226, 16, v155
	v_and_b32_e32 v227, 0xffff0000, v155
	v_fmac_f32_e32 v225, v226, v226
	v_fmac_f32_e32 v225, v227, v227
	v_lshlrev_b32_e32 v226, 16, v156
	v_and_b32_e32 v227, 0xffff0000, v156
	v_fmac_f32_e32 v225, v226, v226
	v_fmac_f32_e32 v225, v227, v227
	v_lshlrev_b32_e32 v226, 16, v157
	v_and_b32_e32 v227, 0xffff0000, v157
	v_fmac_f32_e32 v225, v226, v226
	v_fmac_f32_e32 v225, v227, v227
	v_lshlrev_b32_e32 v226, 16, v158
	v_and_b32_e32 v227, 0xffff0000, v158
	v_fmac_f32_e32 v225, v226, v226
	v_fmac_f32_e32 v225, v227, v227
	v_lshlrev_b32_e32 v226, 16, v159
	v_and_b32_e32 v227, 0xffff0000, v159
	v_fmac_f32_e32 v225, v226, v226
	v_fmac_f32_e32 v225, v227, v227
	ds_write_b32 v245, v225 offset:256
	s_waitcnt lgkmcnt(0)
	ds_read_b32 v228, v246 offset:0
	ds_read_b32 v229, v246 offset:64
	ds_read_b32 v230, v246 offset:128
	ds_read_b32 v231, v246 offset:192
	s_waitcnt lgkmcnt(2)
	v_add_f32_e32 v228, v228, v229
	s_waitcnt lgkmcnt(0)
	v_add_f32_e32 v230, v230, v231
	v_add_f32_e32 v228, v228, v230
	v_sqrt_f32_e32 v228, v228
	s_nop 0
	v_mul_f32_e32 v160, s60, v228
	v_sub_f32_e32 v160, 0, v160
	v_mov_b32_e32 v161, v160
	v_mov_b32_e32 v162, v160
	v_mov_b32_e32 v163, v160
	ds_read_b32 v228, v246 offset:256
	ds_read_b32 v229, v246 offset:320
	ds_read_b32 v230, v246 offset:384
	ds_read_b32 v231, v246 offset:448
	s_waitcnt lgkmcnt(2)
	v_add_f32_e32 v228, v228, v229
	s_waitcnt lgkmcnt(0)
	v_add_f32_e32 v230, v230, v231
	v_add_f32_e32 v228, v228, v230
	v_sqrt_f32_e32 v228, v228
	s_nop 0
	v_mul_f32_e32 v164, s60, v228
	v_sub_f32_e32 v164, 0, v164
	v_mov_b32_e32 v165, v164
	v_mov_b32_e32 v166, v164
	v_mov_b32_e32 v167, v164
	s_waitcnt vmcnt(0) lgkmcnt(0)
	s_barrier
	s_mov_b32 s14, 0
.Lmla_tiles:
	ds_read_b128 v[168:171], v202 offset:0
	ds_read_b128 v[172:175], v203 offset:0
	ds_read_b128 v[176:179], v202 offset:128
	v_mfma_f32_16x16x32_bf16 v[16:19], v[100:103], v[184:187], v[16:19]
	s_mov_b32 m0, s49
	s_nop 0
	buffer_load_dwordx4 v210, s[4:7], s12 offen lds
	v_mfma_f32_16x16x32_bf16 v[48:51], v[108:111], v[184:187], v[48:51]
	s_mov_b32 m0, s50
	s_nop 0
	buffer_load_dwordx4 v211, s[4:7], s12 offen lds
	v_mfma_f32_16x16x32_bf16 v[20:23], v[100:103], v[188:191], v[20:23]
	s_mov_b32 m0, s51
	s_nop 0
	buffer_load_dwordx4 v212, s[4:7], s12 offen lds
	v_mfma_f32_16x16x32_bf16 v[52:55], v[108:111], v[188:191], v[52:55]
	s_mov_b32 m0, s54
	s_nop 0
	buffer_load_dwordx4 v213, s[8:11], s13 offen lds
	v_mfma_f32_16x16x32_bf16 v[24:27], v[100:103], v[192:195], v[24:27]
	s_mov_b32 m0, s55
	s_nop 0
	buffer_load_dwordx4 v214, s[8:11], s13 offen lds
	v_mfma_f32_16x16x32_bf16 v[56:59], v[108:111], v[192:195], v[56:59]
	v_mfma_f32_16x16x32_bf16 v[28:31], v[100:103], v[196:199], v[28:31]
	v_mfma_f32_16x16x32_bf16 v[60:63], v[108:111], v[196:199], v[60:63]
	s_add_i32 s12, s12, 0x30000
	s_add_i32 s13, s13, 0x20000
	ds_read_b128 v[180:183], v203 offset:128
	s_waitcnt lgkmcnt(3)
	v_mfma_f32_16x16x32_bf16 v[64:67], v[168:171], v[112:115], v[160:163]
	v_mfma_f32_16x16x32_bf16 v[68:71], v[168:171], v[136:139], v[164:167]
	ds_read_b128 v[168:171], v202 offset:256
	s_waitcnt lgkmcnt(3)
	v_mfma_f32_16x16x32_bf16 v[64:67], v[172:175], v[116:119], v[64:67]
	v_mfma_f32_16x16x32_bf16 v[68:71], v[172:175], v[140:143], v[68:71]
	ds_read_b128 v[172:175], v203 offset:256
	s_waitcnt lgkmcnt(3)
	v_mfma_f32_16x16x32_bf16 v[64:67], v[176:179], v[120:123], v[64:67]
	v_mfma_f32_16x16x32_bf16 v[68:71], v[176:179], v[144:147], v[68:71]
	ds_read_b128 v[176:179], v202 offset:6144
	s_waitcnt lgkmcnt(3)
	v_mfma_f32_16x16x32_bf16 v[64:67], v[180:183], v[124:127], v[64:67]
	v_mfma_f32_16x16x32_bf16 v[68:71], v[180:183], v[148:151], v[68:71]
	ds_read_b128 v[180:183], v203 offset:6144
	s_waitcnt lgkmcnt(3)
	v_mfma_f32_16x16x32_bf16 v[64:67], v[168:171], v[128:131], v[64:67]
	v_mfma_f32_16x16x32_bf16 v[68:71], v[168:171], v[152:155], v[68:71]
	ds_read_b128 v[168:171], v202 offset:6272
	s_waitcnt lgkmcnt(3)
	v_mfma_f32_16x16x32_bf16 v[64:67], v[172:175], v[132:135], v[64:67]
	v_mfma_f32_16x16x32_bf16 v[68:71], v[172:175], v[156:159], v[68:71]
	ds_read_b128 v[172:175], v203 offset:6272
	s_waitcnt lgkmcnt(3)
	v_mfma_f32_16x16x32_bf16 v[72:75], v[176:179], v[112:115], v[160:163]
	v_mfma_f32_16x16x32_bf16 v[76:79], v[176:179], v[136:139], v[164:167]
	ds_read_b128 v[176:179], v202 offset:6400
	s_waitcnt lgkmcnt(3)
	v_mfma_f32_16x16x32_bf16 v[72:75], v[180:183], v[116:119], v[72:75]
	v_mfma_f32_16x16x32_bf16 v[76:79], v[180:183], v[140:143], v[76:79]
	v_exp_f32_e32 v64, v64
	ds_read_b128 v[180:183], v203 offset:6400
	s_waitcnt lgkmcnt(3)
	v_mfma_f32_16x16x32_bf16 v[72:75], v[168:171], v[120:123], v[72:75]
	v_exp_f32_e32 v65, v65
	v_mfma_f32_16x16x32_bf16 v[76:79], v[168:171], v[144:147], v[76:79]
	v_exp_f32_e32 v66, v66
	ds_read_b128 v[168:171], v202 offset:12288
	s_waitcnt lgkmcnt(3)
	v_mfma_f32_16x16x32_bf16 v[72:75], v[172:175], v[124:127], v[72:75]
	v_exp_f32_e32 v67, v67
	v_mfma_f32_16x16x32_bf16 v[76:79], v[172:175], v[148:151], v[76:79]
	v_exp_f32_e32 v68, v68
	ds_read_b128 v[172:175], v203 offset:12288
	s_waitcnt lgkmcnt(3)
	v_mfma_f32_16x16x32_bf16 v[72:75], v[176:179], v[128:131], v[72:75]
	v_exp_f32_e32 v69, v69
	v_mfma_f32_16x16x32_bf16 v[76:79], v[176:179], v[152:155], v[76:79]
	v_exp_f32_e32 v70, v70
	ds_read_b128 v[176:179], v202 offset:12416
	s_waitcnt lgkmcnt(3)
	v_mfma_f32_16x16x32_bf16 v[72:75], v[180:183], v[132:135], v[72:75]
	v_exp_f32_e32 v71, v71
	v_mfma_f32_16x16x32_bf16 v[76:79], v[180:183], v[156:159], v[76:79]
	v_add_f32_e32 v200, v200, v64
	ds_read_b128 v[180:183], v203 offset:12416
	s_waitcnt lgkmcnt(3)
	v_mfma_f32_16x16x32_bf16 v[80:83], v[168:171], v[112:115], v[160:163]
	v_add_f32_e32 v200, v200, v65
	v_mfma_f32_16x16x32_bf16 v[84:87], v[168:171], v[136:139], v[164:167]
	v_add_f32_e32 v200, v200, v66
	ds_read_b128 v[168:171], v202 offset:12544
	s_waitcnt lgkmcnt(3)
	v_mfma_f32_16x16x32_bf16 v[80:83], v[172:175], v[116:119], v[80:83]
	v_add_f32_e32 v200, v200, v67
	v_mfma_f32_16x16x32_bf16 v[84:87], v[172:175], v[140:143], v[84:87]
	v_add_f32_e32 v201, v201, v68
	ds_read_b128 v[172:175], v203 offset:12544
	s_waitcnt lgkmcnt(3)
	v_mfma_f32_16x16x32_bf16 v[80:83], v[176:179], v[120:123], v[80:83]
	v_add_f32_e32 v201, v201, v69
	v_mfma_f32_16x16x32_bf16 v[84:87], v[176:179], v[144:147], v[84:87]
	v_add_f32_e32 v201, v201, v70
	ds_read_b128 v[176:179], v202 offset:18432
	s_waitcnt lgkmcnt(3)
	v_mfma_f32_16x16x32_bf16 v[80:83], v[180:183], v[124:127], v[80:83]
	v_add_f32_e32 v201, v201, v71
	v_mfma_f32_16x16x32_bf16 v[84:87], v[180:183], v[148:151], v[84:87]
	v_exp_f32_e32 v72, v72
	ds_read_b128 v[180:183], v203 offset:18432
	s_waitcnt lgkmcnt(3)
	v_mfma_f32_16x16x32_bf16 v[80:83], v[168:171], v[128:131], v[80:83]
	v_exp_f32_e32 v73, v73
	v_mfma_f32_16x16x32_bf16 v[84:87], v[168:171], v[152:155], v[84:87]
	v_exp_f32_e32 v74, v74
	ds_read_b128 v[168:171], v202 offset:18560
	s_waitcnt lgkmcnt(3)
	v_mfma_f32_16x16x32_bf16 v[80:83], v[172:175], v[132:135], v[80:83]
	v_exp_f32_e32 v75, v75
	v_mfma_f32_16x16x32_bf16 v[84:87], v[172:175], v[156:159], v[84:87]
	v_exp_f32_e32 v76, v76
	ds_read_b128 v[172:175], v203 offset:18560
	s_waitcnt lgkmcnt(3)
	v_mfma_f32_16x16x32_bf16 v[88:91], v[176:179], v[112:115], v[160:163]
	v_exp_f32_e32 v77, v77
	v_mfma_f32_16x16x32_bf16 v[92:95], v[176:179], v[136:139], v[164:167]
	v_exp_f32_e32 v78, v78
	ds_read_b128 v[176:179], v202 offset:18688
	s_waitcnt lgkmcnt(3)
	v_mfma_f32_16x16x32_bf16 v[88:91], v[180:183], v[116:119], v[88:91]
	v_exp_f32_e32 v79, v79
	v_mfma_f32_16x16x32_bf16 v[92:95], v[180:183], v[140:143], v[92:95]
	v_add_f32_e32 v200, v200, v72
	ds_read_b128 v[180:183], v203 offset:18688
	s_waitcnt lgkmcnt(3)
	v_mfma_f32_16x16x32_bf16 v[88:91], v[168:171], v[120:123], v[88:91]
	v_add_f32_e32 v200, v200, v73
	v_mfma_f32_16x16x32_bf16 v[92:95], v[168:171], v[144:147], v[92:95]
	v_add_f32_e32 v200, v200, v74
	ds_read_b64_tr_b16 v[184:185], v206 offset:49152
	ds_read_b64_tr_b16 v[186:187], v207 offset:49408
	s_waitcnt lgkmcnt(4)
	v_mfma_f32_16x16x32_bf16 v[88:91], v[172:175], v[124:127], v[88:91]
	v_add_f32_e32 v200, v200, v75
	v_mfma_f32_16x16x32_bf16 v[92:95], v[172:175], v[148:151], v[92:95]
	v_add_f32_e32 v201, v201, v76
	ds_read_b64_tr_b16 v[188:189], v208 offset:49152
	ds_read_b64_tr_b16 v[190:191], v209 offset:49408
	s_waitcnt lgkmcnt(5)
	v_mfma_f32_16x16x32_bf16 v[88:91], v[176:179], v[128:131], v[88:91]
	v_add_f32_e32 v201, v201, v77
	v_mfma_f32_16x16x32_bf16 v[92:95], v[176:179], v[152:155], v[92:95]
	v_add_f32_e32 v201, v201, v78
	ds_read_b64_tr_b16 v[192:193], v206 offset:49664
	ds_read_b64_tr_b16 v[194:195], v207 offset:49920
	s_waitcnt lgkmcnt(6)
	v_mfma_f32_16x16x32_bf16 v[88:91], v[180:183], v[132:135], v[88:91]
	v_add_f32_e32 v201, v201, v79
	v_mfma_f32_16x16x32_bf16 v[92:95], v[180:183], v[156:159], v[92:95]
	v_cvt_pk_bf16_f32 v96, v64, v65
	v_cvt_pk_bf16_f32 v97, v66, v67
	v_cvt_pk_bf16_f32 v98, v72, v73
	v_cvt_pk_bf16_f32 v99, v74, v75
	v_cvt_pk_bf16_f32 v104, v68, v69
	v_cvt_pk_bf16_f32 v105, v70, v71
	v_cvt_pk_bf16_f32 v106, v76, v77
	v_cvt_pk_bf16_f32 v107, v78, v79
	ds_read_b64_tr_b16 v[196:197], v208 offset:49664
	ds_read_b64_tr_b16 v[198:199], v209 offset:49920
	s_waitcnt lgkmcnt(6)
	v_mfma_f32_16x16x32_bf16 v[0:3], v[96:99], v[184:187], v[0:3]
	v_exp_f32_e32 v80, v80
	v_exp_f32_e32 v81, v81
	v_mfma_f32_16x16x32_bf16 v[32:35], v[104:107], v[184:187], v[32:35]
	v_exp_f32_e32 v82, v82
	v_exp_f32_e32 v83, v83
	ds_read_b64_tr_b16 v[184:185], v206 offset:50176
	ds_read_b64_tr_b16 v[186:187], v207 offset:50432
	s_waitcnt lgkmcnt(6)
	v_mfma_f32_16x16x32_bf16 v[4:7], v[96:99], v[188:191], v[4:7]
	v_exp_f32_e32 v84, v84
	v_exp_f32_e32 v85, v85
	v_mfma_f32_16x16x32_bf16 v[36:39], v[104:107], v[188:191], v[36:39]
	v_exp_f32_e32 v86, v86
	v_exp_f32_e32 v87, v87
	ds_read_b64_tr_b16 v[188:189], v208 offset:50176
	ds_read_b64_tr_b16 v[190:191], v209 offset:50432
	s_waitcnt lgkmcnt(6)
	v_mfma_f32_16x16x32_bf16 v[8:11], v[96:99], v[192:195], v[8:11]
	v_add_f32_e32 v200, v200, v80
	v_add_f32_e32 v200, v200, v81
	v_mfma_f32_16x16x32_bf16 v[40:43], v[104:107], v[192:195], v[40:43]
	v_add_f32_e32 v200, v200, v82
	v_add_f32_e32 v200, v200, v83
	ds_read_b64_tr_b16 v[192:193], v206 offset:50688
	ds_read_b64_tr_b16 v[194:195], v207 offset:50944
	s_waitcnt lgkmcnt(6)
	v_mfma_f32_16x16x32_bf16 v[12:15], v[96:99], v[196:199], v[12:15]
	v_add_f32_e32 v201, v201, v84
	v_add_f32_e32 v201, v201, v85
	v_mfma_f32_16x16x32_bf16 v[44:47], v[104:107], v[196:199], v[44:47]
	v_add_f32_e32 v201, v201, v86
	v_add_f32_e32 v201, v201, v87
	ds_read_b64_tr_b16 v[196:197], v208 offset:50688
	ds_read_b64_tr_b16 v[198:199], v209 offset:50944
	s_waitcnt lgkmcnt(6)
	v_mfma_f32_16x16x32_bf16 v[16:19], v[96:99], v[184:187], v[16:19]
	v_exp_f32_e32 v88, v88
	v_exp_f32_e32 v89, v89
	v_mfma_f32_16x16x32_bf16 v[48:51], v[104:107], v[184:187], v[48:51]
	v_exp_f32_e32 v90, v90
	v_exp_f32_e32 v91, v91
	ds_read_b64_tr_b16 v[184:185], v206 offset:57344
	ds_read_b64_tr_b16 v[186:187], v207 offset:57600
	s_waitcnt lgkmcnt(6)
	v_mfma_f32_16x16x32_bf16 v[20:23], v[96:99], v[188:191], v[20:23]
	v_exp_f32_e32 v92, v92
	v_exp_f32_e32 v93, v93
	v_mfma_f32_16x16x32_bf16 v[52:55], v[104:107], v[188:191], v[52:55]
	v_exp_f32_e32 v94, v94
	v_exp_f32_e32 v95, v95
	ds_read_b64_tr_b16 v[188:189], v208 offset:57344
	ds_read_b64_tr_b16 v[190:191], v209 offset:57600
	s_waitcnt lgkmcnt(6)
	v_mfma_f32_16x16x32_bf16 v[24:27], v[96:99], v[192:195], v[24:27]
	v_add_f32_e32 v200, v200, v88
	v_add_f32_e32 v200, v200, v89
	v_mfma_f32_16x16x32_bf16 v[56:59], v[104:107], v[192:195], v[56:59]
	v_add_f32_e32 v200, v200, v90
	v_add_f32_e32 v200, v200, v91
	ds_read_b64_tr_b16 v[192:193], v206 offset:57856
	ds_read_b64_tr_b16 v[194:195], v207 offset:58112
	s_waitcnt lgkmcnt(6)
	v_mfma_f32_16x16x32_bf16 v[28:31], v[96:99], v[196:199], v[28:31]
	v_add_f32_e32 v201, v201, v92
	v_add_f32_e32 v201, v201, v93
	v_mfma_f32_16x16x32_bf16 v[60:63], v[104:107], v[196:199], v[60:63]
	v_add_f32_e32 v201, v201, v94
	v_add_f32_e32 v201, v201, v95
	v_cvt_pk_bf16_f32 v100, v80, v81
	v_cvt_pk_bf16_f32 v101, v82, v83
	v_cvt_pk_bf16_f32 v102, v88, v89
	v_cvt_pk_bf16_f32 v103, v90, v91
	v_cvt_pk_bf16_f32 v108, v84, v85
	v_cvt_pk_bf16_f32 v109, v86, v87
	v_cvt_pk_bf16_f32 v110, v92, v93
	v_cvt_pk_bf16_f32 v111, v94, v95
	ds_read_b64_tr_b16 v[196:197], v208 offset:57856
	ds_read_b64_tr_b16 v[198:199], v209 offset:58112
	s_waitcnt lgkmcnt(6)
	v_mfma_f32_16x16x32_bf16 v[0:3], v[100:103], v[184:187], v[0:3]
	v_mfma_f32_16x16x32_bf16 v[32:35], v[108:111], v[184:187], v[32:35]
	ds_read_b64_tr_b16 v[184:185], v206 offset:58368
	ds_read_b64_tr_b16 v[186:187], v207 offset:58624
	s_waitcnt lgkmcnt(6)
	v_mfma_f32_16x16x32_bf16 v[4:7], v[100:103], v[188:191], v[4:7]
	v_mfma_f32_16x16x32_bf16 v[36:39], v[108:111], v[188:191], v[36:39]
	ds_read_b64_tr_b16 v[188:189], v208 offset:58368
	ds_read_b64_tr_b16 v[190:191], v209 offset:58624
	s_waitcnt lgkmcnt(6)
	v_mfma_f32_16x16x32_bf16 v[8:11], v[100:103], v[192:195], v[8:11]
	v_mfma_f32_16x16x32_bf16 v[40:43], v[108:111], v[192:195], v[40:43]
	ds_read_b64_tr_b16 v[192:193], v206 offset:58880
	ds_read_b64_tr_b16 v[194:195], v207 offset:59136
	s_waitcnt lgkmcnt(6)
	v_mfma_f32_16x16x32_bf16 v[12:15], v[100:103], v[196:199], v[12:15]
	v_mfma_f32_16x16x32_bf16 v[44:47], v[108:111], v[196:199], v[44:47]
	ds_read_b64_tr_b16 v[196:197], v208 offset:58880
	ds_read_b64_tr_b16 v[198:199], v209 offset:59136
	s_waitcnt vmcnt(0) lgkmcnt(0)
	s_barrier
	ds_read_b128 v[168:171], v202 offset:24576
	ds_read_b128 v[172:175], v203 offset:24576
	ds_read_b128 v[176:179], v202 offset:24704
	v_mfma_f32_16x16x32_bf16 v[16:19], v[100:103], v[184:187], v[16:19]
	s_mov_b32 m0, s46
	s_nop 0
	buffer_load_dwordx4 v210, s[4:7], s12 offen lds
	v_mfma_f32_16x16x32_bf16 v[48:51], v[108:111], v[184:187], v[48:51]
	s_mov_b32 m0, s47
	s_nop 0
	buffer_load_dwordx4 v211, s[4:7], s12 offen lds
	v_mfma_f32_16x16x32_bf16 v[20:23], v[100:103], v[188:191], v[20:23]
	s_mov_b32 m0, s48
	s_nop 0
	buffer_load_dwordx4 v212, s[4:7], s12 offen lds
	v_mfma_f32_16x16x32_bf16 v[52:55], v[108:111], v[188:191], v[52:55]
	s_mov_b32 m0, s52
	s_nop 0
	buffer_load_dwordx4 v213, s[8:11], s13 offen lds
	v_mfma_f32_16x16x32_bf16 v[24:27], v[100:103], v[192:195], v[24:27]
	s_mov_b32 m0, s53
	s_nop 0
	buffer_load_dwordx4 v214, s[8:11], s13 offen lds
	v_mfma_f32_16x16x32_bf16 v[56:59], v[108:111], v[192:195], v[56:59]
	v_mfma_f32_16x16x32_bf16 v[28:31], v[100:103], v[196:199], v[28:31]
	v_mfma_f32_16x16x32_bf16 v[60:63], v[108:111], v[196:199], v[60:63]
	s_add_i32 s12, s12, 0x30000
	s_add_i32 s13, s13, 0x20000
	ds_read_b128 v[180:183], v203 offset:24704
	s_waitcnt lgkmcnt(3)
	v_mfma_f32_16x16x32_bf16 v[64:67], v[168:171], v[112:115], v[160:163]
	v_mfma_f32_16x16x32_bf16 v[68:71], v[168:171], v[136:139], v[164:167]
	ds_read_b128 v[168:171], v202 offset:24832
	s_waitcnt lgkmcnt(3)
	v_mfma_f32_16x16x32_bf16 v[64:67], v[172:175], v[116:119], v[64:67]
	v_mfma_f32_16x16x32_bf16 v[68:71], v[172:175], v[140:143], v[68:71]
	ds_read_b128 v[172:175], v203 offset:24832
	s_waitcnt lgkmcnt(3)
	v_mfma_f32_16x16x32_bf16 v[64:67], v[176:179], v[120:123], v[64:67]
	v_mfma_f32_16x16x32_bf16 v[68:71], v[176:179], v[144:147], v[68:71]
	ds_read_b128 v[176:179], v202 offset:30720
	s_waitcnt lgkmcnt(3)
	v_mfma_f32_16x16x32_bf16 v[64:67], v[180:183], v[124:127], v[64:67]
	v_mfma_f32_16x16x32_bf16 v[68:71], v[180:183], v[148:151], v[68:71]
	ds_read_b128 v[180:183], v203 offset:30720
	s_waitcnt lgkmcnt(3)
	v_mfma_f32_16x16x32_bf16 v[64:67], v[168:171], v[128:131], v[64:67]
	v_mfma_f32_16x16x32_bf16 v[68:71], v[168:171], v[152:155], v[68:71]
	ds_read_b128 v[168:171], v202 offset:30848
	s_waitcnt lgkmcnt(3)
	v_mfma_f32_16x16x32_bf16 v[64:67], v[172:175], v[132:135], v[64:67]
	v_mfma_f32_16x16x32_bf16 v[68:71], v[172:175], v[156:159], v[68:71]
	ds_read_b128 v[172:175], v203 offset:30848
	s_waitcnt lgkmcnt(3)
	v_mfma_f32_16x16x32_bf16 v[72:75], v[176:179], v[112:115], v[160:163]
	v_mfma_f32_16x16x32_bf16 v[76:79], v[176:179], v[136:139], v[164:167]
	ds_read_b128 v[176:179], v202 offset:30976
	s_waitcnt lgkmcnt(3)
	v_mfma_f32_16x16x32_bf16 v[72:75], v[180:183], v[116:119], v[72:75]
	v_mfma_f32_16x16x32_bf16 v[76:79], v[180:183], v[140:143], v[76:79]
	v_exp_f32_e32 v64, v64
	ds_read_b128 v[180:183], v203 offset:30976
	s_waitcnt lgkmcnt(3)
	v_mfma_f32_16x16x32_bf16 v[72:75], v[168:171], v[120:123], v[72:75]
	v_exp_f32_e32 v65, v65
	v_mfma_f32_16x16x32_bf16 v[76:79], v[168:171], v[144:147], v[76:79]
	v_exp_f32_e32 v66, v66
	ds_read_b128 v[168:171], v202 offset:36864
	s_waitcnt lgkmcnt(3)
	v_mfma_f32_16x16x32_bf16 v[72:75], v[172:175], v[124:127], v[72:75]
	v_exp_f32_e32 v67, v67
	v_mfma_f32_16x16x32_bf16 v[76:79], v[172:175], v[148:151], v[76:79]
	v_exp_f32_e32 v68, v68
	ds_read_b128 v[172:175], v203 offset:36864
	s_waitcnt lgkmcnt(3)
	v_mfma_f32_16x16x32_bf16 v[72:75], v[176:179], v[128:131], v[72:75]
	v_exp_f32_e32 v69, v69
	v_mfma_f32_16x16x32_bf16 v[76:79], v[176:179], v[152:155], v[76:79]
	v_exp_f32_e32 v70, v70
	ds_read_b128 v[176:179], v202 offset:36992
	s_waitcnt lgkmcnt(3)
	v_mfma_f32_16x16x32_bf16 v[72:75], v[180:183], v[132:135], v[72:75]
	v_exp_f32_e32 v71, v71
	v_mfma_f32_16x16x32_bf16 v[76:79], v[180:183], v[156:159], v[76:79]
	v_add_f32_e32 v200, v200, v64
	ds_read_b128 v[180:183], v203 offset:36992
	s_waitcnt lgkmcnt(3)
	v_mfma_f32_16x16x32_bf16 v[80:83], v[168:171], v[112:115], v[160:163]
	v_add_f32_e32 v200, v200, v65
	v_mfma_f32_16x16x32_bf16 v[84:87], v[168:171], v[136:139], v[164:167]
	v_add_f32_e32 v200, v200, v66
	ds_read_b128 v[168:171], v202 offset:37120
	s_waitcnt lgkmcnt(3)
	v_mfma_f32_16x16x32_bf16 v[80:83], v[172:175], v[116:119], v[80:83]
	v_add_f32_e32 v200, v200, v67
	v_mfma_f32_16x16x32_bf16 v[84:87], v[172:175], v[140:143], v[84:87]
	v_add_f32_e32 v201, v201, v68
	ds_read_b128 v[172:175], v203 offset:37120
	s_waitcnt lgkmcnt(3)
	v_mfma_f32_16x16x32_bf16 v[80:83], v[176:179], v[120:123], v[80:83]
	v_add_f32_e32 v201, v201, v69
	v_mfma_f32_16x16x32_bf16 v[84:87], v[176:179], v[144:147], v[84:87]
	v_add_f32_e32 v201, v201, v70
	ds_read_b128 v[176:179], v202 offset:43008
	s_waitcnt lgkmcnt(3)
	v_mfma_f32_16x16x32_bf16 v[80:83], v[180:183], v[124:127], v[80:83]
	v_add_f32_e32 v201, v201, v71
	v_mfma_f32_16x16x32_bf16 v[84:87], v[180:183], v[148:151], v[84:87]
	v_exp_f32_e32 v72, v72
	ds_read_b128 v[180:183], v203 offset:43008
	s_waitcnt lgkmcnt(3)
	v_mfma_f32_16x16x32_bf16 v[80:83], v[168:171], v[128:131], v[80:83]
	v_exp_f32_e32 v73, v73
	v_mfma_f32_16x16x32_bf16 v[84:87], v[168:171], v[152:155], v[84:87]
	v_exp_f32_e32 v74, v74
	ds_read_b128 v[168:171], v202 offset:43136
	s_waitcnt lgkmcnt(3)
	v_mfma_f32_16x16x32_bf16 v[80:83], v[172:175], v[132:135], v[80:83]
	v_exp_f32_e32 v75, v75
	v_mfma_f32_16x16x32_bf16 v[84:87], v[172:175], v[156:159], v[84:87]
	v_exp_f32_e32 v76, v76
	ds_read_b128 v[172:175], v203 offset:43136
	s_waitcnt lgkmcnt(3)
	v_mfma_f32_16x16x32_bf16 v[88:91], v[176:179], v[112:115], v[160:163]
	v_exp_f32_e32 v77, v77
	v_mfma_f32_16x16x32_bf16 v[92:95], v[176:179], v[136:139], v[164:167]
	v_exp_f32_e32 v78, v78
	ds_read_b128 v[176:179], v202 offset:43264
	s_waitcnt lgkmcnt(3)
	v_mfma_f32_16x16x32_bf16 v[88:91], v[180:183], v[116:119], v[88:91]
	v_exp_f32_e32 v79, v79
	v_mfma_f32_16x16x32_bf16 v[92:95], v[180:183], v[140:143], v[92:95]
	v_add_f32_e32 v200, v200, v72
	ds_read_b128 v[180:183], v203 offset:43264
	s_waitcnt lgkmcnt(3)
	v_mfma_f32_16x16x32_bf16 v[88:91], v[168:171], v[120:123], v[88:91]
	v_add_f32_e32 v200, v200, v73
	v_mfma_f32_16x16x32_bf16 v[92:95], v[168:171], v[144:147], v[92:95]
	v_add_f32_e32 v200, v200, v74
	ds_read_b64_tr_b16 v[184:185], v250 offset:49152
	ds_read_b64_tr_b16 v[186:187], v251 offset:49408
	s_waitcnt lgkmcnt(4)
	v_mfma_f32_16x16x32_bf16 v[88:91], v[172:175], v[124:127], v[88:91]
	v_add_f32_e32 v200, v200, v75
	v_mfma_f32_16x16x32_bf16 v[92:95], v[172:175], v[148:151], v[92:95]
	v_add_f32_e32 v201, v201, v76
	ds_read_b64_tr_b16 v[188:189], v252 offset:49152
	ds_read_b64_tr_b16 v[190:191], v253 offset:49408
	s_waitcnt lgkmcnt(5)
	v_mfma_f32_16x16x32_bf16 v[88:91], v[176:179], v[128:131], v[88:91]
	v_add_f32_e32 v201, v201, v77
	v_mfma_f32_16x16x32_bf16 v[92:95], v[176:179], v[152:155], v[92:95]
	v_add_f32_e32 v201, v201, v78
	ds_read_b64_tr_b16 v[192:193], v250 offset:49664
	ds_read_b64_tr_b16 v[194:195], v251 offset:49920
	s_waitcnt lgkmcnt(6)
	v_mfma_f32_16x16x32_bf16 v[88:91], v[180:183], v[132:135], v[88:91]
	v_add_f32_e32 v201, v201, v79
	v_mfma_f32_16x16x32_bf16 v[92:95], v[180:183], v[156:159], v[92:95]
	v_cvt_pk_bf16_f32 v96, v64, v65
	v_cvt_pk_bf16_f32 v97, v66, v67
	v_cvt_pk_bf16_f32 v98, v72, v73
	v_cvt_pk_bf16_f32 v99, v74, v75
	v_cvt_pk_bf16_f32 v104, v68, v69
	v_cvt_pk_bf16_f32 v105, v70, v71
	v_cvt_pk_bf16_f32 v106, v76, v77
	v_cvt_pk_bf16_f32 v107, v78, v79
	ds_read_b64_tr_b16 v[196:197], v252 offset:49664
	ds_read_b64_tr_b16 v[198:199], v253 offset:49920
	s_waitcnt lgkmcnt(6)
	v_mfma_f32_16x16x32_bf16 v[0:3], v[96:99], v[184:187], v[0:3]
	v_exp_f32_e32 v80, v80
	v_exp_f32_e32 v81, v81
	v_mfma_f32_16x16x32_bf16 v[32:35], v[104:107], v[184:187], v[32:35]
	v_exp_f32_e32 v82, v82
	v_exp_f32_e32 v83, v83
	ds_read_b64_tr_b16 v[184:185], v250 offset:50176
	ds_read_b64_tr_b16 v[186:187], v251 offset:50432
	s_waitcnt lgkmcnt(6)
	v_mfma_f32_16x16x32_bf16 v[4:7], v[96:99], v[188:191], v[4:7]
	v_exp_f32_e32 v84, v84
	v_exp_f32_e32 v85, v85
	v_mfma_f32_16x16x32_bf16 v[36:39], v[104:107], v[188:191], v[36:39]
	v_exp_f32_e32 v86, v86
	v_exp_f32_e32 v87, v87
	ds_read_b64_tr_b16 v[188:189], v252 offset:50176
	ds_read_b64_tr_b16 v[190:191], v253 offset:50432
	s_waitcnt lgkmcnt(6)
	v_mfma_f32_16x16x32_bf16 v[8:11], v[96:99], v[192:195], v[8:11]
	v_add_f32_e32 v200, v200, v80
	v_add_f32_e32 v200, v200, v81
	v_mfma_f32_16x16x32_bf16 v[40:43], v[104:107], v[192:195], v[40:43]
	v_add_f32_e32 v200, v200, v82
	v_add_f32_e32 v200, v200, v83
	ds_read_b64_tr_b16 v[192:193], v250 offset:50688
	ds_read_b64_tr_b16 v[194:195], v251 offset:50944
	s_waitcnt lgkmcnt(6)
	v_mfma_f32_16x16x32_bf16 v[12:15], v[96:99], v[196:199], v[12:15]
	v_add_f32_e32 v201, v201, v84
	v_add_f32_e32 v201, v201, v85
	v_mfma_f32_16x16x32_bf16 v[44:47], v[104:107], v[196:199], v[44:47]
	v_add_f32_e32 v201, v201, v86
	v_add_f32_e32 v201, v201, v87
	ds_read_b64_tr_b16 v[196:197], v252 offset:50688
	ds_read_b64_tr_b16 v[198:199], v253 offset:50944
	s_waitcnt lgkmcnt(6)
	v_mfma_f32_16x16x32_bf16 v[16:19], v[96:99], v[184:187], v[16:19]
	v_exp_f32_e32 v88, v88
	v_exp_f32_e32 v89, v89
	v_mfma_f32_16x16x32_bf16 v[48:51], v[104:107], v[184:187], v[48:51]
	v_exp_f32_e32 v90, v90
	v_exp_f32_e32 v91, v91
	ds_read_b64_tr_b16 v[184:185], v250 offset:57344
	ds_read_b64_tr_b16 v[186:187], v251 offset:57600
	s_waitcnt lgkmcnt(6)
	v_mfma_f32_16x16x32_bf16 v[20:23], v[96:99], v[188:191], v[20:23]
	v_exp_f32_e32 v92, v92
	v_exp_f32_e32 v93, v93
	v_mfma_f32_16x16x32_bf16 v[52:55], v[104:107], v[188:191], v[52:55]
	v_exp_f32_e32 v94, v94
	v_exp_f32_e32 v95, v95
	ds_read_b64_tr_b16 v[188:189], v252 offset:57344
	ds_read_b64_tr_b16 v[190:191], v253 offset:57600
	s_waitcnt lgkmcnt(6)
	v_mfma_f32_16x16x32_bf16 v[24:27], v[96:99], v[192:195], v[24:27]
	v_add_f32_e32 v200, v200, v88
	v_add_f32_e32 v200, v200, v89
	v_mfma_f32_16x16x32_bf16 v[56:59], v[104:107], v[192:195], v[56:59]
	v_add_f32_e32 v200, v200, v90
	v_add_f32_e32 v200, v200, v91
	ds_read_b64_tr_b16 v[192:193], v250 offset:57856
	ds_read_b64_tr_b16 v[194:195], v251 offset:58112
	s_waitcnt lgkmcnt(6)
	v_mfma_f32_16x16x32_bf16 v[28:31], v[96:99], v[196:199], v[28:31]
	v_add_f32_e32 v201, v201, v92
	v_add_f32_e32 v201, v201, v93
	v_mfma_f32_16x16x32_bf16 v[60:63], v[104:107], v[196:199], v[60:63]
	v_add_f32_e32 v201, v201, v94
	v_add_f32_e32 v201, v201, v95
	v_cvt_pk_bf16_f32 v100, v80, v81
	v_cvt_pk_bf16_f32 v101, v82, v83
	v_cvt_pk_bf16_f32 v102, v88, v89
	v_cvt_pk_bf16_f32 v103, v90, v91
	v_cvt_pk_bf16_f32 v108, v84, v85
	v_cvt_pk_bf16_f32 v109, v86, v87
	v_cvt_pk_bf16_f32 v110, v92, v93
	v_cvt_pk_bf16_f32 v111, v94, v95
	ds_read_b64_tr_b16 v[196:197], v252 offset:57856
	ds_read_b64_tr_b16 v[198:199], v253 offset:58112
	s_waitcnt lgkmcnt(6)
	v_mfma_f32_16x16x32_bf16 v[0:3], v[100:103], v[184:187], v[0:3]
	v_mfma_f32_16x16x32_bf16 v[32:35], v[108:111], v[184:187], v[32:35]
	ds_read_b64_tr_b16 v[184:185], v250 offset:58368
	ds_read_b64_tr_b16 v[186:187], v251 offset:58624
	s_waitcnt lgkmcnt(6)
	v_mfma_f32_16x16x32_bf16 v[4:7], v[100:103], v[188:191], v[4:7]
	v_mfma_f32_16x16x32_bf16 v[36:39], v[108:111], v[188:191], v[36:39]
	ds_read_b64_tr_b16 v[188:189], v252 offset:58368
	ds_read_b64_tr_b16 v[190:191], v253 offset:58624
	s_waitcnt lgkmcnt(6)
	v_mfma_f32_16x16x32_bf16 v[8:11], v[100:103], v[192:195], v[8:11]
	v_mfma_f32_16x16x32_bf16 v[40:43], v[108:111], v[192:195], v[40:43]
	ds_read_b64_tr_b16 v[192:193], v250 offset:58880
	ds_read_b64_tr_b16 v[194:195], v251 offset:59136
	s_waitcnt lgkmcnt(6)
	v_mfma_f32_16x16x32_bf16 v[12:15], v[100:103], v[196:199], v[12:15]
	v_mfma_f32_16x16x32_bf16 v[44:47], v[108:111], v[196:199], v[44:47]
	ds_read_b64_tr_b16 v[196:197], v252 offset:58880
	ds_read_b64_tr_b16 v[198:199], v253 offset:59136
	s_waitcnt vmcnt(0) lgkmcnt(0)
	s_barrier
	s_add_i32 s14, s14, 2
	s_cmpk_lt_u32 s14, 256
	s_cbranch_scc1 .Lmla_tiles
	v_mfma_f32_16x16x32_bf16 v[16:19], v[100:103], v[184:187], v[16:19]
	v_mfma_f32_16x16x32_bf16 v[48:51], v[108:111], v[184:187], v[48:51]
	v_mfma_f32_16x16x32_bf16 v[20:23], v[100:103], v[188:191], v[20:23]
	v_mfma_f32_16x16x32_bf16 v[52:55], v[108:111], v[188:191], v[52:55]
	v_mfma_f32_16x16x32_bf16 v[24:27], v[100:103], v[192:195], v[24:27]
	v_mfma_f32_16x16x32_bf16 v[56:59], v[108:111], v[192:195], v[56:59]
	v_mfma_f32_16x16x32_bf16 v[28:31], v[100:103], v[196:199], v[28:31]
	v_mfma_f32_16x16x32_bf16 v[60:63], v[108:111], v[196:199], v[60:63]
	s_nop 7
	ds_write_b32 v245, v200 offset:0
	ds_write_b32 v245, v201 offset:256
	s_waitcnt lgkmcnt(0)
	ds_read_b128 v[218:221], v247 offset:0
	ds_read_b128 v[222:225], v247 offset:64
	ds_read_b128 v[226:229], v247 offset:128
	ds_read_b128 v[230:233], v247 offset:192
	s_waitcnt lgkmcnt(2)
	v_add_f32_e32 v218, v218, v222
	s_waitcnt lgkmcnt(0)
	v_add_f32_e32 v226, v226, v230
	v_add_f32_e32 v218, v218, v226
	v_rcp_f32_e32 v234, v218
	v_add_f32_e32 v219, v219, v223
	v_add_f32_e32 v227, v227, v231
	v_add_f32_e32 v219, v219, v227
	v_rcp_f32_e32 v235, v219
	v_add_f32_e32 v220, v220, v224
	v_add_f32_e32 v228, v228, v232
	v_add_f32_e32 v220, v220, v228
	v_rcp_f32_e32 v236, v220
	v_add_f32_e32 v221, v221, v225
	v_add_f32_e32 v229, v229, v233
	v_add_f32_e32 v221, v221, v229
	v_rcp_f32_e32 v237, v221
	ds_read_b128 v[218:221], v247 offset:256
	ds_read_b128 v[222:225], v247 offset:320
	ds_read_b128 v[226:229], v247 offset:384
	ds_read_b128 v[230:233], v247 offset:448
	s_waitcnt lgkmcnt(2)
	v_add_f32_e32 v218, v218, v222
	s_waitcnt lgkmcnt(0)
	v_add_f32_e32 v226, v226, v230
	v_add_f32_e32 v218, v218, v226
	v_rcp_f32_e32 v238, v218
	v_add_f32_e32 v219, v219, v223
	v_add_f32_e32 v227, v227, v231
	v_add_f32_e32 v219, v219, v227
	v_rcp_f32_e32 v239, v219
	v_add_f32_e32 v220, v220, v224
	v_add_f32_e32 v228, v228, v232
	v_add_f32_e32 v220, v220, v228
	v_rcp_f32_e32 v240, v220
	v_add_f32_e32 v221, v221, v225
	v_add_f32_e32 v229, v229, v233
	v_add_f32_e32 v221, v221, v229
	v_rcp_f32_e32 v241, v221
	s_nop 0
	v_add_u32_e32 v242, 0, v248
	v_mul_f32_e32 v0, v0, v234
	v_cvt_pk_bf16_f32 v243, v0, v249
	global_store_short v242, v243, s[18:19] offset:0
	v_mul_f32_e32 v4, v4, v234
	v_cvt_pk_bf16_f32 v244, v4, v249
	global_store_short v242, v244, s[18:19] offset:32
	v_mul_f32_e32 v8, v8, v234
	v_cvt_pk_bf16_f32 v243, v8, v249
	global_store_short v242, v243, s[18:19] offset:64
	v_mul_f32_e32 v12, v12, v234
	v_cvt_pk_bf16_f32 v244, v12, v249
	global_store_short v242, v244, s[18:19] offset:96
	v_mul_f32_e32 v16, v16, v234
	v_cvt_pk_bf16_f32 v243, v16, v249
	global_store_short v242, v243, s[18:19] offset:128
	v_mul_f32_e32 v20, v20, v234
	v_cvt_pk_bf16_f32 v244, v20, v249
	global_store_short v242, v244, s[18:19] offset:160
	v_mul_f32_e32 v24, v24, v234
	v_cvt_pk_bf16_f32 v243, v24, v249
	global_store_short v242, v243, s[18:19] offset:192
	v_mul_f32_e32 v28, v28, v234
	v_cvt_pk_bf16_f32 v244, v28, v249
	global_store_short v242, v244, s[18:19] offset:224
	v_add_u32_e32 v242, 4096, v248
	v_mul_f32_e32 v1, v1, v235
	v_cvt_pk_bf16_f32 v243, v1, v249
	global_store_short v242, v243, s[18:19] offset:0
	v_mul_f32_e32 v5, v5, v235
	v_cvt_pk_bf16_f32 v244, v5, v249
	global_store_short v242, v244, s[18:19] offset:32
	v_mul_f32_e32 v9, v9, v235
	v_cvt_pk_bf16_f32 v243, v9, v249
	global_store_short v242, v243, s[18:19] offset:64
	v_mul_f32_e32 v13, v13, v235
	v_cvt_pk_bf16_f32 v244, v13, v249
	global_store_short v242, v244, s[18:19] offset:96
	v_mul_f32_e32 v17, v17, v235
	v_cvt_pk_bf16_f32 v243, v17, v249
	global_store_short v242, v243, s[18:19] offset:128
	v_mul_f32_e32 v21, v21, v235
	v_cvt_pk_bf16_f32 v244, v21, v249
	global_store_short v242, v244, s[18:19] offset:160
	v_mul_f32_e32 v25, v25, v235
	v_cvt_pk_bf16_f32 v243, v25, v249
	global_store_short v242, v243, s[18:19] offset:192
	v_mul_f32_e32 v29, v29, v235
	v_cvt_pk_bf16_f32 v244, v29, v249
	global_store_short v242, v244, s[18:19] offset:224
	v_add_u32_e32 v242, 8192, v248
	v_mul_f32_e32 v2, v2, v236
	v_cvt_pk_bf16_f32 v243, v2, v249
	global_store_short v242, v243, s[18:19] offset:0
	v_mul_f32_e32 v6, v6, v236
	v_cvt_pk_bf16_f32 v244, v6, v249
	global_store_short v242, v244, s[18:19] offset:32
	v_mul_f32_e32 v10, v10, v236
	v_cvt_pk_bf16_f32 v243, v10, v249
	global_store_short v242, v243, s[18:19] offset:64
	v_mul_f32_e32 v14, v14, v236
	v_cvt_pk_bf16_f32 v244, v14, v249
	global_store_short v242, v244, s[18:19] offset:96
	v_mul_f32_e32 v18, v18, v236
	v_cvt_pk_bf16_f32 v243, v18, v249
	global_store_short v242, v243, s[18:19] offset:128
	v_mul_f32_e32 v22, v22, v236
	v_cvt_pk_bf16_f32 v244, v22, v249
	global_store_short v242, v244, s[18:19] offset:160
	v_mul_f32_e32 v26, v26, v236
	v_cvt_pk_bf16_f32 v243, v26, v249
	global_store_short v242, v243, s[18:19] offset:192
	v_mul_f32_e32 v30, v30, v236
	v_cvt_pk_bf16_f32 v244, v30, v249
	global_store_short v242, v244, s[18:19] offset:224
	v_add_u32_e32 v242, 12288, v248
	v_mul_f32_e32 v3, v3, v237
	v_cvt_pk_bf16_f32 v243, v3, v249
	global_store_short v242, v243, s[18:19] offset:0
	v_mul_f32_e32 v7, v7, v237
	v_cvt_pk_bf16_f32 v244, v7, v249
	global_store_short v242, v244, s[18:19] offset:32
	v_mul_f32_e32 v11, v11, v237
	v_cvt_pk_bf16_f32 v243, v11, v249
	global_store_short v242, v243, s[18:19] offset:64
	v_mul_f32_e32 v15, v15, v237
	v_cvt_pk_bf16_f32 v244, v15, v249
	global_store_short v242, v244, s[18:19] offset:96
	v_mul_f32_e32 v19, v19, v237
	v_cvt_pk_bf16_f32 v243, v19, v249
	global_store_short v242, v243, s[18:19] offset:128
	v_mul_f32_e32 v23, v23, v237
	v_cvt_pk_bf16_f32 v244, v23, v249
	global_store_short v242, v244, s[18:19] offset:160
	v_mul_f32_e32 v27, v27, v237
	v_cvt_pk_bf16_f32 v243, v27, v249
	global_store_short v242, v243, s[18:19] offset:192
	v_mul_f32_e32 v31, v31, v237
	v_cvt_pk_bf16_f32 v244, v31, v249
	global_store_short v242, v244, s[18:19] offset:224
	v_add_u32_e32 v242, 65536, v248
	v_mul_f32_e32 v32, v32, v238
	v_cvt_pk_bf16_f32 v243, v32, v249
	global_store_short v242, v243, s[18:19] offset:0
	v_mul_f32_e32 v36, v36, v238
	v_cvt_pk_bf16_f32 v244, v36, v249
	global_store_short v242, v244, s[18:19] offset:32
	v_mul_f32_e32 v40, v40, v238
	v_cvt_pk_bf16_f32 v243, v40, v249
	global_store_short v242, v243, s[18:19] offset:64
	v_mul_f32_e32 v44, v44, v238
	v_cvt_pk_bf16_f32 v244, v44, v249
	global_store_short v242, v244, s[18:19] offset:96
	v_mul_f32_e32 v48, v48, v238
	v_cvt_pk_bf16_f32 v243, v48, v249
	global_store_short v242, v243, s[18:19] offset:128
	v_mul_f32_e32 v52, v52, v238
	v_cvt_pk_bf16_f32 v244, v52, v249
	global_store_short v242, v244, s[18:19] offset:160
	v_mul_f32_e32 v56, v56, v238
	v_cvt_pk_bf16_f32 v243, v56, v249
	global_store_short v242, v243, s[18:19] offset:192
	v_mul_f32_e32 v60, v60, v238
	v_cvt_pk_bf16_f32 v244, v60, v249
	global_store_short v242, v244, s[18:19] offset:224
	v_add_u32_e32 v242, 69632, v248
	v_mul_f32_e32 v33, v33, v239
	v_cvt_pk_bf16_f32 v243, v33, v249
	global_store_short v242, v243, s[18:19] offset:0
	v_mul_f32_e32 v37, v37, v239
	v_cvt_pk_bf16_f32 v244, v37, v249
	global_store_short v242, v244, s[18:19] offset:32
	v_mul_f32_e32 v41, v41, v239
	v_cvt_pk_bf16_f32 v243, v41, v249
	global_store_short v242, v243, s[18:19] offset:64
	v_mul_f32_e32 v45, v45, v239
	v_cvt_pk_bf16_f32 v244, v45, v249
	global_store_short v242, v244, s[18:19] offset:96
	v_mul_f32_e32 v49, v49, v239
	v_cvt_pk_bf16_f32 v243, v49, v249
	global_store_short v242, v243, s[18:19] offset:128
	v_mul_f32_e32 v53, v53, v239
	v_cvt_pk_bf16_f32 v244, v53, v249
	global_store_short v242, v244, s[18:19] offset:160
	v_mul_f32_e32 v57, v57, v239
	v_cvt_pk_bf16_f32 v243, v57, v249
	global_store_short v242, v243, s[18:19] offset:192
	v_mul_f32_e32 v61, v61, v239
	v_cvt_pk_bf16_f32 v244, v61, v249
	global_store_short v242, v244, s[18:19] offset:224
	v_add_u32_e32 v242, 73728, v248
	v_mul_f32_e32 v34, v34, v240
	v_cvt_pk_bf16_f32 v243, v34, v249
	global_store_short v242, v243, s[18:19] offset:0
	v_mul_f32_e32 v38, v38, v240
	v_cvt_pk_bf16_f32 v244, v38, v249
	global_store_short v242, v244, s[18:19] offset:32
	v_mul_f32_e32 v42, v42, v240
	v_cvt_pk_bf16_f32 v243, v42, v249
	global_store_short v242, v243, s[18:19] offset:64
	v_mul_f32_e32 v46, v46, v240
	v_cvt_pk_bf16_f32 v244, v46, v249
	global_store_short v242, v244, s[18:19] offset:96
	v_mul_f32_e32 v50, v50, v240
	v_cvt_pk_bf16_f32 v243, v50, v249
	global_store_short v242, v243, s[18:19] offset:128
	v_mul_f32_e32 v54, v54, v240
	v_cvt_pk_bf16_f32 v244, v54, v249
	global_store_short v242, v244, s[18:19] offset:160
	v_mul_f32_e32 v58, v58, v240
	v_cvt_pk_bf16_f32 v243, v58, v249
	global_store_short v242, v243, s[18:19] offset:192
	v_mul_f32_e32 v62, v62, v240
	v_cvt_pk_bf16_f32 v244, v62, v249
	global_store_short v242, v244, s[18:19] offset:224
	v_add_u32_e32 v242, 77824, v248
	v_mul_f32_e32 v35, v35, v241
	v_cvt_pk_bf16_f32 v243, v35, v249
	global_store_short v242, v243, s[18:19] offset:0
	v_mul_f32_e32 v39, v39, v241
	v_cvt_pk_bf16_f32 v244, v39, v249
	global_store_short v242, v244, s[18:19] offset:32
	v_mul_f32_e32 v43, v43, v241
	v_cvt_pk_bf16_f32 v243, v43, v249
	global_store_short v242, v243, s[18:19] offset:64
	v_mul_f32_e32 v47, v47, v241
	v_cvt_pk_bf16_f32 v244, v47, v249
	global_store_short v242, v244, s[18:19] offset:96
	v_mul_f32_e32 v51, v51, v241
	v_cvt_pk_bf16_f32 v243, v51, v249
	global_store_short v242, v243, s[18:19] offset:128
	v_mul_f32_e32 v55, v55, v241
	v_cvt_pk_bf16_f32 v244, v55, v249
	global_store_short v242, v244, s[18:19] offset:160
	v_mul_f32_e32 v59, v59, v241
	v_cvt_pk_bf16_f32 v243, v59, v249
	global_store_short v242, v243, s[18:19] offset:192
	v_mul_f32_e32 v63, v63, v241
	v_cvt_pk_bf16_f32 v244, v63, v249
	global_store_short v242, v244, s[18:19] offset:224
	s_add_i32 s76, s76, s34
	s_cmpk_gt_i32 s76, 0x1ff
	s_cbranch_scc0 .Lmla_unit
